# back-edge rotation (guide 7.11) on the four GEMM K-loops: counter/pointer/exit-test SALU moved into the tail of the last compute part, fragment-read address first at the loop head
# baseline (speedup 1.0000x reference)
.LBB0_278:
	s_add_i32 s73, 0, 0x10000
	v_add_u32_e32 v2, s73, v191
	s_add_i32 s76, 0, 0x14000
	ds_read_b128 v[132:135], v2
	ds_read_b128 v[136:139], v2 offset:1024
	ds_read_b128 v[140:143], v2 offset:2048
	ds_read_b128 v[144:147], v2 offset:3072
	v_add_u32_e32 v2, s76, v191
	ds_read_b128 v[148:151], v2
	ds_read_b128 v[152:155], v2 offset:1024
	ds_read_b128 v[156:159], v2 offset:2048
	ds_read_b128 v[160:163], v2 offset:3072
	v_lshl_add_u64 v[188:189], s[6:7], 0, v[174:175]
	s_add_i32 m0, s47, 0xc000
	ds_read_b128 v[176:179], v197
	ds_read_b128 v[180:183], v197 offset:1024
	ds_read_b128 v[184:187], v197 offset:2048
	ds_read_b128 v[192:195], v197 offset:3072
	ds_read_b128 v[198:201], v197 offset:4096
	ds_read_b128 v[202:205], v197 offset:5120
	ds_read_b128 v[206:209], v197 offset:6144
	ds_read_b128 v[220:223], v197 offset:7168
	global_load_lds_dwordx4 v[188:189], off
	v_lshl_add_u64 v[188:189], s[6:7], 0, v[172:173]
	s_add_i32 m0, s47, 0xe000
	s_nop 0
	global_load_lds_dwordx4 v[188:189], off
	s_add_u32 s8, s6, 0xfff80080
	s_addc_u32 s9, s7, -1
	s_cmp_eq_u32 s72, 28
	s_cselect_b32 s39, s43, s9
	s_cselect_b32 s38, s52, s8
	s_cselect_b32 s9, s45, s67
	s_cselect_b32 s8, s65, s66
	s_waitcnt vmcnt(8)
	s_waitcnt lgkmcnt(0)
	s_barrier
	s_setprio 1
	s_waitcnt lgkmcnt(0)
	v_mfma_f32_16x16x32_bf16 v[124:127], v[132:135], v[176:179], v[124:127]
	v_mfma_f32_16x16x32_bf16 v[128:131], v[140:143], v[176:179], v[128:131]
	v_mfma_f32_16x16x32_bf16 v[108:111], v[132:135], v[184:187], v[108:111]
	v_mfma_f32_16x16x32_bf16 v[112:115], v[140:143], v[184:187], v[112:115]
	v_mfma_f32_16x16x32_bf16 v[92:95], v[132:135], v[198:201], v[92:95]
	v_mfma_f32_16x16x32_bf16 v[96:99], v[140:143], v[198:201], v[96:99]
	v_mfma_f32_16x16x32_bf16 v[76:79], v[132:135], v[206:209], v[76:79]
	v_mfma_f32_16x16x32_bf16 v[80:83], v[140:143], v[206:209], v[80:83]
	v_mfma_f32_16x16x32_bf16 v[124:127], v[136:139], v[180:183], v[124:127]
	v_mfma_f32_16x16x32_bf16 v[128:131], v[144:147], v[180:183], v[128:131]
	v_mfma_f32_16x16x32_bf16 v[108:111], v[136:139], v[192:195], v[108:111]
	v_mfma_f32_16x16x32_bf16 v[112:115], v[144:147], v[192:195], v[112:115]
	v_mfma_f32_16x16x32_bf16 v[92:95], v[136:139], v[202:205], v[92:95]
	v_mfma_f32_16x16x32_bf16 v[96:99], v[144:147], v[202:205], v[96:99]
	v_mfma_f32_16x16x32_bf16 v[76:79], v[136:139], v[220:223], v[76:79]
	v_mfma_f32_16x16x32_bf16 v[80:83], v[144:147], v[220:223], v[80:83]
	s_setprio 0
	s_setprio 1
	v_mfma_f32_16x16x32_bf16 v[116:119], v[148:151], v[176:179], v[116:119]
	v_mfma_f32_16x16x32_bf16 v[120:123], v[156:159], v[176:179], v[120:123]
	v_mfma_f32_16x16x32_bf16 v[100:103], v[148:151], v[184:187], v[100:103]
	v_mfma_f32_16x16x32_bf16 v[104:107], v[156:159], v[184:187], v[104:107]
	v_mfma_f32_16x16x32_bf16 v[84:87], v[148:151], v[198:201], v[84:87]
	v_mfma_f32_16x16x32_bf16 v[88:91], v[156:159], v[198:201], v[88:91]
	v_mfma_f32_16x16x32_bf16 v[68:71], v[148:151], v[206:209], v[68:71]
	v_mfma_f32_16x16x32_bf16 v[72:75], v[156:159], v[206:209], v[72:75]
	v_mfma_f32_16x16x32_bf16 v[116:119], v[152:155], v[180:183], v[116:119]
	v_mfma_f32_16x16x32_bf16 v[120:123], v[160:163], v[180:183], v[120:123]
	v_mfma_f32_16x16x32_bf16 v[100:103], v[152:155], v[192:195], v[100:103]
	v_mfma_f32_16x16x32_bf16 v[104:107], v[160:163], v[192:195], v[104:107]
	v_mfma_f32_16x16x32_bf16 v[84:87], v[152:155], v[202:205], v[84:87]
	v_mfma_f32_16x16x32_bf16 v[88:91], v[160:163], v[202:205], v[88:91]
	v_mfma_f32_16x16x32_bf16 v[68:71], v[152:155], v[220:223], v[68:71]
	v_mfma_f32_16x16x32_bf16 v[72:75], v[160:163], v[220:223], v[72:75]
	s_setprio 0
	s_barrier
	s_add_i32 s73, s73, s46
	v_lshl_add_u64 v[188:189], s[8:9], 0, v[168:169]
	s_mov_b32 m0, s73
	ds_read_b128 v[176:179], v197 offset:16384
	ds_read_b128 v[180:183], v197 offset:17408
	ds_read_b128 v[184:187], v197 offset:18432
	ds_read_b128 v[192:195], v197 offset:19456
	ds_read_b128 v[198:201], v197 offset:20480
	ds_read_b128 v[202:205], v197 offset:21504
	ds_read_b128 v[206:209], v197 offset:22528
	ds_read_b128 v[220:223], v197 offset:23552
	global_load_lds_dwordx4 v[188:189], off
	s_add_i32 m0, s73, 0x2000
	s_add_u32 s74, s8, 0x80000
	v_lshl_add_u64 v[210:211], s[8:9], 0, v[164:165]
	s_addc_u32 s75, s9, 0
	s_add_i32 s73, s76, s46
	global_load_lds_dwordx4 v[210:211], off
	v_lshl_add_u64 v[216:217], s[74:75], 0, v[168:169]
	s_mov_b32 m0, s73
	v_lshl_add_u64 v[224:225], s[38:39], 0, v[166:167]
	global_load_lds_dwordx4 v[216:217], off
	v_lshl_add_u64 v[216:217], s[74:75], 0, v[164:165]
	s_add_i32 m0, s73, 0x2000
	s_mov_b64 s[76:77], 0x80
	global_load_lds_dwordx4 v[216:217], off
	v_lshl_add_u64 v[216:217], s[38:39], 0, v[170:171]
	s_mov_b32 m0, s47
	s_nop 0
	global_load_lds_dwordx4 v[216:217], off
	s_mov_b32 m0, s48
	s_nop 0
	global_load_lds_dwordx4 v[224:225], off
	s_waitcnt vmcnt(8)
	s_waitcnt lgkmcnt(0)
	s_barrier
	s_setprio 1
	s_waitcnt lgkmcnt(0)
	v_mfma_f32_16x16x32_bf16 v[60:63], v[132:135], v[176:179], v[60:63]
	v_mfma_f32_16x16x32_bf16 v[64:67], v[140:143], v[176:179], v[64:67]
	v_mfma_f32_16x16x32_bf16 v[44:47], v[132:135], v[184:187], v[44:47]
	v_mfma_f32_16x16x32_bf16 v[48:51], v[140:143], v[184:187], v[48:51]
	v_mfma_f32_16x16x32_bf16 v[28:31], v[132:135], v[198:201], v[28:31]
	v_mfma_f32_16x16x32_bf16 v[32:35], v[140:143], v[198:201], v[32:35]
	v_mfma_f32_16x16x32_bf16 v[12:15], v[132:135], v[206:209], v[12:15]
	v_mfma_f32_16x16x32_bf16 v[16:19], v[140:143], v[206:209], v[16:19]
	v_mfma_f32_16x16x32_bf16 v[60:63], v[136:139], v[180:183], v[60:63]
	v_mfma_f32_16x16x32_bf16 v[64:67], v[144:147], v[180:183], v[64:67]
	v_mfma_f32_16x16x32_bf16 v[44:47], v[136:139], v[192:195], v[44:47]
	v_mfma_f32_16x16x32_bf16 v[48:51], v[144:147], v[192:195], v[48:51]
	v_mfma_f32_16x16x32_bf16 v[28:31], v[136:139], v[202:205], v[28:31]
	v_mfma_f32_16x16x32_bf16 v[32:35], v[144:147], v[202:205], v[32:35]
	v_mfma_f32_16x16x32_bf16 v[12:15], v[136:139], v[220:223], v[12:15]
	v_mfma_f32_16x16x32_bf16 v[16:19], v[144:147], v[220:223], v[16:19]
	s_setprio 0
	s_setprio 1
	v_mfma_f32_16x16x32_bf16 v[52:55], v[148:151], v[176:179], v[52:55]
	v_mfma_f32_16x16x32_bf16 v[56:59], v[156:159], v[176:179], v[56:59]
	v_mfma_f32_16x16x32_bf16 v[36:39], v[148:151], v[184:187], v[36:39]
	v_mfma_f32_16x16x32_bf16 v[40:43], v[156:159], v[184:187], v[40:43]
	v_mfma_f32_16x16x32_bf16 v[20:23], v[148:151], v[198:201], v[20:23]
	v_mfma_f32_16x16x32_bf16 v[24:27], v[156:159], v[198:201], v[24:27]
	v_mfma_f32_16x16x32_bf16 v[4:7], v[148:151], v[206:209], v[4:7]
	v_mfma_f32_16x16x32_bf16 v[8:11], v[156:159], v[206:209], v[8:11]
	v_mfma_f32_16x16x32_bf16 v[52:55], v[152:155], v[180:183], v[52:55]
	v_mfma_f32_16x16x32_bf16 v[56:59], v[160:163], v[180:183], v[56:59]
	v_mfma_f32_16x16x32_bf16 v[36:39], v[152:155], v[192:195], v[36:39]
	v_mfma_f32_16x16x32_bf16 v[40:43], v[160:163], v[192:195], v[40:43]
	v_mfma_f32_16x16x32_bf16 v[20:23], v[152:155], v[202:205], v[20:23]
	v_mfma_f32_16x16x32_bf16 v[24:27], v[160:163], v[202:205], v[24:27]
	v_mfma_f32_16x16x32_bf16 v[4:7], v[152:155], v[220:223], v[4:7]
	v_mfma_f32_16x16x32_bf16 v[8:11], v[160:163], v[220:223], v[8:11]
	s_setprio 0
	s_barrier
	s_add_i32 s73, 0, 0x18000
	v_add_u32_e32 v2, s73, v191
	s_add_i32 s74, 0, 0x1c000
	ds_read_b128 v[132:135], v2
	ds_read_b128 v[136:139], v2 offset:1024
	ds_read_b128 v[140:143], v2 offset:2048
	ds_read_b128 v[144:147], v2 offset:3072
	v_add_u32_e32 v2, s74, v191
	ds_read_b128 v[148:151], v2
	ds_read_b128 v[152:155], v2 offset:1024
	ds_read_b128 v[156:159], v2 offset:2048
	ds_read_b128 v[160:163], v2 offset:3072
	s_add_u32 s38, s38, 0x80000
	s_addc_u32 s39, s39, 0
	s_mov_b32 m0, s49
	v_lshl_add_u64 v[226:227], s[38:39], 0, v[170:171]
	ds_read_b128 v[176:179], v197 offset:32768
	ds_read_b128 v[180:183], v197 offset:33792
	ds_read_b128 v[184:187], v197 offset:34816
	ds_read_b128 v[192:195], v197 offset:35840
	ds_read_b128 v[198:201], v197 offset:36864
	ds_read_b128 v[202:205], v197 offset:37888
	ds_read_b128 v[206:209], v197 offset:38912
	ds_read_b128 v[220:223], v197 offset:39936
	global_load_lds_dwordx4 v[226:227], off
	v_lshl_add_u64 v[226:227], s[38:39], 0, v[166:167]
	s_mov_b32 m0, s54
	s_nop 0
	global_load_lds_dwordx4 v[226:227], off
	s_waitcnt vmcnt(8)
	s_waitcnt lgkmcnt(0)
	s_barrier
	s_setprio 1
	s_waitcnt lgkmcnt(0)
	v_mfma_f32_16x16x32_bf16 v[124:127], v[132:135], v[176:179], v[124:127]
	v_mfma_f32_16x16x32_bf16 v[128:131], v[140:143], v[176:179], v[128:131]
	v_mfma_f32_16x16x32_bf16 v[108:111], v[132:135], v[184:187], v[108:111]
	v_mfma_f32_16x16x32_bf16 v[112:115], v[140:143], v[184:187], v[112:115]
	v_mfma_f32_16x16x32_bf16 v[92:95], v[132:135], v[198:201], v[92:95]
	v_mfma_f32_16x16x32_bf16 v[96:99], v[140:143], v[198:201], v[96:99]
	v_mfma_f32_16x16x32_bf16 v[76:79], v[132:135], v[206:209], v[76:79]
	v_mfma_f32_16x16x32_bf16 v[80:83], v[140:143], v[206:209], v[80:83]
	v_mfma_f32_16x16x32_bf16 v[124:127], v[136:139], v[180:183], v[124:127]
	v_mfma_f32_16x16x32_bf16 v[128:131], v[144:147], v[180:183], v[128:131]
	v_mfma_f32_16x16x32_bf16 v[108:111], v[136:139], v[192:195], v[108:111]
	v_mfma_f32_16x16x32_bf16 v[112:115], v[144:147], v[192:195], v[112:115]
	v_mfma_f32_16x16x32_bf16 v[92:95], v[136:139], v[202:205], v[92:95]
	v_mfma_f32_16x16x32_bf16 v[96:99], v[144:147], v[202:205], v[96:99]
	v_mfma_f32_16x16x32_bf16 v[76:79], v[136:139], v[220:223], v[76:79]
	v_mfma_f32_16x16x32_bf16 v[80:83], v[144:147], v[220:223], v[80:83]
	s_setprio 0
	s_setprio 1
	v_mfma_f32_16x16x32_bf16 v[116:119], v[148:151], v[176:179], v[116:119]
	v_mfma_f32_16x16x32_bf16 v[120:123], v[156:159], v[176:179], v[120:123]
	v_mfma_f32_16x16x32_bf16 v[100:103], v[148:151], v[184:187], v[100:103]
	v_mfma_f32_16x16x32_bf16 v[104:107], v[156:159], v[184:187], v[104:107]
	v_mfma_f32_16x16x32_bf16 v[84:87], v[148:151], v[198:201], v[84:87]
	v_mfma_f32_16x16x32_bf16 v[88:91], v[156:159], v[198:201], v[88:91]
	v_mfma_f32_16x16x32_bf16 v[68:71], v[148:151], v[206:209], v[68:71]
	v_mfma_f32_16x16x32_bf16 v[72:75], v[156:159], v[206:209], v[72:75]
	v_mfma_f32_16x16x32_bf16 v[116:119], v[152:155], v[180:183], v[116:119]
	v_mfma_f32_16x16x32_bf16 v[120:123], v[160:163], v[180:183], v[120:123]
	v_mfma_f32_16x16x32_bf16 v[100:103], v[152:155], v[192:195], v[100:103]
	v_mfma_f32_16x16x32_bf16 v[104:107], v[160:163], v[192:195], v[104:107]
	v_mfma_f32_16x16x32_bf16 v[84:87], v[152:155], v[202:205], v[84:87]
	v_mfma_f32_16x16x32_bf16 v[88:91], v[160:163], v[202:205], v[88:91]
	v_mfma_f32_16x16x32_bf16 v[68:71], v[152:155], v[220:223], v[68:71]
	v_mfma_f32_16x16x32_bf16 v[72:75], v[160:163], v[220:223], v[72:75]
	s_setprio 0
	s_barrier
	s_add_i32 s38, s73, s46
	v_lshl_add_u64 v[188:189], v[188:189], 0, s[76:77]
	s_mov_b32 m0, s38
	ds_read_b128 v[176:179], v197 offset:49152
	ds_read_b128 v[180:183], v197 offset:50176
	ds_read_b128 v[184:187], v197 offset:51200
	ds_read_b128 v[192:195], v197 offset:52224
	ds_read_b128 v[198:201], v197 offset:53248
	ds_read_b128 v[202:205], v197 offset:54272
	ds_read_b128 v[206:209], v197 offset:55296
	ds_read_b128 v[220:223], v197 offset:56320
	global_load_lds_dwordx4 v[188:189], off
	s_add_i32 m0, s38, 0x2000
	s_add_u32 s8, s8, 0x80080
	v_lshl_add_u64 v[188:189], v[210:211], 0, s[76:77]
	s_addc_u32 s9, s9, 0
	s_add_i32 s38, s74, s46
	global_load_lds_dwordx4 v[188:189], off
	v_lshl_add_u64 v[188:189], s[8:9], 0, v[168:169]
	s_mov_b32 m0, s38
	s_nop 0
	global_load_lds_dwordx4 v[188:189], off
	v_lshl_add_u64 v[188:189], s[8:9], 0, v[164:165]
	s_add_i32 m0, s38, 0x2000
	s_nop 0
	global_load_lds_dwordx4 v[188:189], off
	v_lshl_add_u64 v[188:189], v[216:217], 0, s[76:77]
	s_mov_b32 m0, s59
	s_nop 0
	global_load_lds_dwordx4 v[188:189], off
	v_lshl_add_u64 v[188:189], v[224:225], 0, s[76:77]
	s_mov_b32 m0, s60
	s_nop 0
	global_load_lds_dwordx4 v[188:189], off
	s_waitcnt vmcnt(8)
	s_waitcnt lgkmcnt(0)
	s_barrier
	s_setprio 1
	s_waitcnt lgkmcnt(0)
	v_mfma_f32_16x16x32_bf16 v[60:63], v[132:135], v[176:179], v[60:63]
	v_mfma_f32_16x16x32_bf16 v[64:67], v[140:143], v[176:179], v[64:67]
	v_mfma_f32_16x16x32_bf16 v[44:47], v[132:135], v[184:187], v[44:47]
	v_mfma_f32_16x16x32_bf16 v[48:51], v[140:143], v[184:187], v[48:51]
	v_mfma_f32_16x16x32_bf16 v[28:31], v[132:135], v[198:201], v[28:31]
	v_mfma_f32_16x16x32_bf16 v[32:35], v[140:143], v[198:201], v[32:35]
	v_mfma_f32_16x16x32_bf16 v[12:15], v[132:135], v[206:209], v[12:15]
	v_mfma_f32_16x16x32_bf16 v[16:19], v[140:143], v[206:209], v[16:19]
	v_mfma_f32_16x16x32_bf16 v[60:63], v[136:139], v[180:183], v[60:63]
	v_mfma_f32_16x16x32_bf16 v[64:67], v[144:147], v[180:183], v[64:67]
	v_mfma_f32_16x16x32_bf16 v[44:47], v[136:139], v[192:195], v[44:47]
	v_mfma_f32_16x16x32_bf16 v[48:51], v[144:147], v[192:195], v[48:51]
	v_mfma_f32_16x16x32_bf16 v[28:31], v[136:139], v[202:205], v[28:31]
	v_mfma_f32_16x16x32_bf16 v[32:35], v[144:147], v[202:205], v[32:35]
	v_mfma_f32_16x16x32_bf16 v[12:15], v[136:139], v[220:223], v[12:15]
	v_mfma_f32_16x16x32_bf16 v[16:19], v[144:147], v[220:223], v[16:19]
	s_setprio 0
	s_setprio 1
	v_mfma_f32_16x16x32_bf16 v[52:55], v[148:151], v[176:179], v[52:55]
	v_mfma_f32_16x16x32_bf16 v[56:59], v[156:159], v[176:179], v[56:59]
	v_mfma_f32_16x16x32_bf16 v[36:39], v[148:151], v[184:187], v[36:39]
	v_mfma_f32_16x16x32_bf16 v[40:43], v[156:159], v[184:187], v[40:43]
	v_mfma_f32_16x16x32_bf16 v[20:23], v[148:151], v[198:201], v[20:23]
	v_mfma_f32_16x16x32_bf16 v[24:27], v[156:159], v[198:201], v[24:27]
	v_mfma_f32_16x16x32_bf16 v[4:7], v[148:151], v[206:209], v[4:7]
	v_mfma_f32_16x16x32_bf16 v[8:11], v[156:159], v[206:209], v[8:11]
	v_mfma_f32_16x16x32_bf16 v[52:55], v[152:155], v[180:183], v[52:55]
	v_mfma_f32_16x16x32_bf16 v[56:59], v[160:163], v[180:183], v[56:59]
	v_mfma_f32_16x16x32_bf16 v[36:39], v[152:155], v[192:195], v[36:39]
	v_mfma_f32_16x16x32_bf16 v[40:43], v[160:163], v[192:195], v[40:43]
	s_add_i32 s72, s72, 2
	s_add_u32 s66, s66, 0x100
	s_addc_u32 s67, s67, 0
	s_add_u32 s6, s6, 0x100
	s_addc_u32 s7, s7, 0
	s_cmp_gt_u32 s72, 29
	v_mfma_f32_16x16x32_bf16 v[20:23], v[152:155], v[202:205], v[20:23]
	v_mfma_f32_16x16x32_bf16 v[24:27], v[160:163], v[202:205], v[24:27]
	v_mfma_f32_16x16x32_bf16 v[4:7], v[152:155], v[220:223], v[4:7]
	v_mfma_f32_16x16x32_bf16 v[8:11], v[160:163], v[220:223], v[8:11]
	s_setprio 0
	s_barrier
	s_cbranch_scc0 .LBB0_278
	s_and_b64 vcc, exec, s[18:19]
	s_cbranch_vccz .LBB0_281
	s_barrier

.LBB0_1229:
	s_add_i32 s56, 0, 0x10000
	v_add_u32_e32 v2, s56, v216
	s_add_i32 s58, 0, 0x14000
	ds_read_b128 v[132:135], v2
	ds_read_b128 v[136:139], v2 offset:1024
	ds_read_b128 v[140:143], v2 offset:2048
	ds_read_b128 v[144:147], v2 offset:3072
	v_add_u32_e32 v2, s58, v216
	ds_read_b128 v[148:151], v2
	ds_read_b128 v[152:155], v2 offset:1024
	ds_read_b128 v[156:159], v2 offset:2048
	ds_read_b128 v[160:163], v2 offset:3072
	v_lshl_add_u64 v[208:209], s[18:19], 0, v[198:199]
	s_add_i32 m0, s29, 0xc000
	ds_read_b128 v[164:167], v217
	ds_read_b128 v[168:171], v217 offset:1024
	ds_read_b128 v[172:175], v217 offset:2048
	ds_read_b128 v[176:179], v217 offset:3072
	ds_read_b128 v[180:183], v217 offset:4096
	ds_read_b128 v[184:187], v217 offset:5120
	ds_read_b128 v[200:203], v217 offset:6144
	ds_read_b128 v[204:207], v217 offset:7168
	global_load_lds_dwordx4 v[208:209], off
	v_lshl_add_u64 v[208:209], s[18:19], 0, v[196:197]
	s_add_i32 m0, s29, 0xe000
	s_nop 0
	global_load_lds_dwordx4 v[208:209], off
	s_add_u32 s20, s18, 0xfff80080
	s_addc_u32 s21, s19, -1
	s_cmp_eq_u32 s52, 28
	s_cselect_b32 s23, s13, s21
	s_cselect_b32 s22, s46, s20
	s_cselect_b32 s21, s11, s49
	s_cselect_b32 s20, s47, s48
	s_waitcnt vmcnt(8)
	s_waitcnt lgkmcnt(0)
	s_barrier
	s_setprio 1
	s_waitcnt lgkmcnt(0)
	v_mfma_f32_16x16x32_bf16 v[128:131], v[132:135], v[164:167], v[128:131]
	v_mfma_f32_16x16x32_bf16 v[124:127], v[140:143], v[164:167], v[124:127]
	v_mfma_f32_16x16x32_bf16 v[112:115], v[132:135], v[172:175], v[112:115]
	v_mfma_f32_16x16x32_bf16 v[108:111], v[140:143], v[172:175], v[108:111]
	v_mfma_f32_16x16x32_bf16 v[96:99], v[132:135], v[180:183], v[96:99]
	v_mfma_f32_16x16x32_bf16 v[92:95], v[140:143], v[180:183], v[92:95]
	v_mfma_f32_16x16x32_bf16 v[80:83], v[132:135], v[200:203], v[80:83]
	v_mfma_f32_16x16x32_bf16 v[76:79], v[140:143], v[200:203], v[76:79]
	v_mfma_f32_16x16x32_bf16 v[128:131], v[136:139], v[168:171], v[128:131]
	v_mfma_f32_16x16x32_bf16 v[124:127], v[144:147], v[168:171], v[124:127]
	v_mfma_f32_16x16x32_bf16 v[112:115], v[136:139], v[176:179], v[112:115]
	v_mfma_f32_16x16x32_bf16 v[108:111], v[144:147], v[176:179], v[108:111]
	v_mfma_f32_16x16x32_bf16 v[96:99], v[136:139], v[184:187], v[96:99]
	v_mfma_f32_16x16x32_bf16 v[92:95], v[144:147], v[184:187], v[92:95]
	v_mfma_f32_16x16x32_bf16 v[80:83], v[136:139], v[204:207], v[80:83]
	v_mfma_f32_16x16x32_bf16 v[76:79], v[144:147], v[204:207], v[76:79]
	s_setprio 0
	s_setprio 1
	v_mfma_f32_16x16x32_bf16 v[120:123], v[148:151], v[164:167], v[120:123]
	v_mfma_f32_16x16x32_bf16 v[116:119], v[156:159], v[164:167], v[116:119]
	v_mfma_f32_16x16x32_bf16 v[104:107], v[148:151], v[172:175], v[104:107]
	v_mfma_f32_16x16x32_bf16 v[100:103], v[156:159], v[172:175], v[100:103]
	v_mfma_f32_16x16x32_bf16 v[88:91], v[148:151], v[180:183], v[88:91]
	v_mfma_f32_16x16x32_bf16 v[84:87], v[156:159], v[180:183], v[84:87]
	v_mfma_f32_16x16x32_bf16 v[72:75], v[148:151], v[200:203], v[72:75]
	v_mfma_f32_16x16x32_bf16 v[68:71], v[156:159], v[200:203], v[68:71]
	v_mfma_f32_16x16x32_bf16 v[120:123], v[152:155], v[168:171], v[120:123]
	v_mfma_f32_16x16x32_bf16 v[116:119], v[160:163], v[168:171], v[116:119]
	v_mfma_f32_16x16x32_bf16 v[104:107], v[152:155], v[176:179], v[104:107]
	v_mfma_f32_16x16x32_bf16 v[100:103], v[160:163], v[176:179], v[100:103]
	v_mfma_f32_16x16x32_bf16 v[88:91], v[152:155], v[184:187], v[88:91]
	v_mfma_f32_16x16x32_bf16 v[84:87], v[160:163], v[184:187], v[84:87]
	v_mfma_f32_16x16x32_bf16 v[72:75], v[152:155], v[204:207], v[72:75]
	v_mfma_f32_16x16x32_bf16 v[68:71], v[160:163], v[204:207], v[68:71]
	s_setprio 0
	s_barrier
	s_add_i32 s56, s56, s28
	v_lshl_add_u64 v[208:209], s[20:21], 0, v[192:193]
	s_mov_b32 m0, s56
	ds_read_b128 v[164:167], v217 offset:16384
	ds_read_b128 v[168:171], v217 offset:17408
	ds_read_b128 v[172:175], v217 offset:18432
	ds_read_b128 v[176:179], v217 offset:19456
	ds_read_b128 v[180:183], v217 offset:20480
	ds_read_b128 v[184:187], v217 offset:21504
	ds_read_b128 v[200:203], v217 offset:22528
	ds_read_b128 v[204:207], v217 offset:23552
	global_load_lds_dwordx4 v[208:209], off
	s_add_i32 m0, s56, 0x2000
	s_add_u32 s56, s20, 0x80000
	v_lshl_add_u64 v[210:211], s[20:21], 0, v[188:189]
	s_addc_u32 s57, s21, 0
	s_add_i32 s58, s58, s28
	global_load_lds_dwordx4 v[210:211], off
	v_lshl_add_u64 v[220:221], s[56:57], 0, v[192:193]
	s_mov_b32 m0, s58
	v_lshl_add_u64 v[222:223], s[22:23], 0, v[190:191]
	global_load_lds_dwordx4 v[220:221], off
	v_lshl_add_u64 v[220:221], s[56:57], 0, v[188:189]
	s_add_i32 m0, s58, 0x2000
	s_nop 0
	global_load_lds_dwordx4 v[220:221], off
	v_lshl_add_u64 v[220:221], s[22:23], 0, v[194:195]
	s_mov_b32 m0, s29
	s_nop 0
	global_load_lds_dwordx4 v[220:221], off
	s_mov_b32 m0, s30
	s_nop 0
	global_load_lds_dwordx4 v[222:223], off
	s_waitcnt vmcnt(8)
	s_waitcnt lgkmcnt(0)
	s_barrier
	s_setprio 1
	s_waitcnt lgkmcnt(0)
	v_mfma_f32_16x16x32_bf16 v[64:67], v[132:135], v[164:167], v[64:67]
	v_mfma_f32_16x16x32_bf16 v[60:63], v[140:143], v[164:167], v[60:63]
	v_mfma_f32_16x16x32_bf16 v[48:51], v[132:135], v[172:175], v[48:51]
	v_mfma_f32_16x16x32_bf16 v[44:47], v[140:143], v[172:175], v[44:47]
	v_mfma_f32_16x16x32_bf16 v[32:35], v[132:135], v[180:183], v[32:35]
	v_mfma_f32_16x16x32_bf16 v[28:31], v[140:143], v[180:183], v[28:31]
	v_mfma_f32_16x16x32_bf16 v[16:19], v[132:135], v[200:203], v[16:19]
	v_mfma_f32_16x16x32_bf16 v[12:15], v[140:143], v[200:203], v[12:15]
	v_mfma_f32_16x16x32_bf16 v[64:67], v[136:139], v[168:171], v[64:67]
	v_mfma_f32_16x16x32_bf16 v[60:63], v[144:147], v[168:171], v[60:63]
	v_mfma_f32_16x16x32_bf16 v[48:51], v[136:139], v[176:179], v[48:51]
	v_mfma_f32_16x16x32_bf16 v[44:47], v[144:147], v[176:179], v[44:47]
	v_mfma_f32_16x16x32_bf16 v[32:35], v[136:139], v[184:187], v[32:35]
	v_mfma_f32_16x16x32_bf16 v[28:31], v[144:147], v[184:187], v[28:31]
	v_mfma_f32_16x16x32_bf16 v[16:19], v[136:139], v[204:207], v[16:19]
	v_mfma_f32_16x16x32_bf16 v[12:15], v[144:147], v[204:207], v[12:15]
	s_setprio 0
	s_setprio 1
	v_mfma_f32_16x16x32_bf16 v[56:59], v[148:151], v[164:167], v[56:59]
	v_mfma_f32_16x16x32_bf16 v[52:55], v[156:159], v[164:167], v[52:55]
	v_mfma_f32_16x16x32_bf16 v[40:43], v[148:151], v[172:175], v[40:43]
	v_mfma_f32_16x16x32_bf16 v[36:39], v[156:159], v[172:175], v[36:39]
	v_mfma_f32_16x16x32_bf16 v[24:27], v[148:151], v[180:183], v[24:27]
	v_mfma_f32_16x16x32_bf16 v[20:23], v[156:159], v[180:183], v[20:23]
	v_mfma_f32_16x16x32_bf16 v[8:11], v[148:151], v[200:203], v[8:11]
	v_mfma_f32_16x16x32_bf16 v[4:7], v[156:159], v[200:203], v[4:7]
	v_mfma_f32_16x16x32_bf16 v[56:59], v[152:155], v[168:171], v[56:59]
	v_mfma_f32_16x16x32_bf16 v[52:55], v[160:163], v[168:171], v[52:55]
	v_mfma_f32_16x16x32_bf16 v[40:43], v[152:155], v[176:179], v[40:43]
	v_mfma_f32_16x16x32_bf16 v[36:39], v[160:163], v[176:179], v[36:39]
	v_mfma_f32_16x16x32_bf16 v[24:27], v[152:155], v[184:187], v[24:27]
	v_mfma_f32_16x16x32_bf16 v[20:23], v[160:163], v[184:187], v[20:23]
	v_mfma_f32_16x16x32_bf16 v[8:11], v[152:155], v[204:207], v[8:11]
	v_mfma_f32_16x16x32_bf16 v[4:7], v[160:163], v[204:207], v[4:7]
	s_setprio 0
	s_barrier
	s_add_i32 s56, 0, 0x18000
	v_add_u32_e32 v2, s56, v216
	s_add_i32 s57, 0, 0x1c000
	ds_read_b128 v[132:135], v2
	ds_read_b128 v[136:139], v2 offset:1024
	ds_read_b128 v[140:143], v2 offset:2048
	ds_read_b128 v[144:147], v2 offset:3072
	v_add_u32_e32 v2, s57, v216
	ds_read_b128 v[148:151], v2
	ds_read_b128 v[152:155], v2 offset:1024
	ds_read_b128 v[156:159], v2 offset:2048
	ds_read_b128 v[160:163], v2 offset:3072
	s_add_u32 s22, s22, 0x80000
	s_addc_u32 s23, s23, 0
	s_mov_b32 m0, s31
	v_lshl_add_u64 v[224:225], s[22:23], 0, v[194:195]
	ds_read_b128 v[164:167], v217 offset:32768
	ds_read_b128 v[168:171], v217 offset:33792
	ds_read_b128 v[172:175], v217 offset:34816
	ds_read_b128 v[176:179], v217 offset:35840
	ds_read_b128 v[180:183], v217 offset:36864
	ds_read_b128 v[184:187], v217 offset:37888
	ds_read_b128 v[200:203], v217 offset:38912
	ds_read_b128 v[204:207], v217 offset:39936
	global_load_lds_dwordx4 v[224:225], off
	v_lshl_add_u64 v[224:225], s[22:23], 0, v[190:191]
	s_mov_b32 m0, s34
	s_nop 0
	global_load_lds_dwordx4 v[224:225], off
	s_waitcnt vmcnt(8)
	s_waitcnt lgkmcnt(0)
	s_barrier
	s_setprio 1
	s_waitcnt lgkmcnt(0)
	v_mfma_f32_16x16x32_bf16 v[128:131], v[132:135], v[164:167], v[128:131]
	v_mfma_f32_16x16x32_bf16 v[124:127], v[140:143], v[164:167], v[124:127]
	v_mfma_f32_16x16x32_bf16 v[112:115], v[132:135], v[172:175], v[112:115]
	v_mfma_f32_16x16x32_bf16 v[108:111], v[140:143], v[172:175], v[108:111]
	v_mfma_f32_16x16x32_bf16 v[96:99], v[132:135], v[180:183], v[96:99]
	v_mfma_f32_16x16x32_bf16 v[92:95], v[140:143], v[180:183], v[92:95]
	v_mfma_f32_16x16x32_bf16 v[80:83], v[132:135], v[200:203], v[80:83]
	v_mfma_f32_16x16x32_bf16 v[76:79], v[140:143], v[200:203], v[76:79]
	v_mfma_f32_16x16x32_bf16 v[128:131], v[136:139], v[168:171], v[128:131]
	v_mfma_f32_16x16x32_bf16 v[124:127], v[144:147], v[168:171], v[124:127]
	v_mfma_f32_16x16x32_bf16 v[112:115], v[136:139], v[176:179], v[112:115]
	v_mfma_f32_16x16x32_bf16 v[108:111], v[144:147], v[176:179], v[108:111]
	v_mfma_f32_16x16x32_bf16 v[96:99], v[136:139], v[184:187], v[96:99]
	v_mfma_f32_16x16x32_bf16 v[92:95], v[144:147], v[184:187], v[92:95]
	v_mfma_f32_16x16x32_bf16 v[80:83], v[136:139], v[204:207], v[80:83]
	v_mfma_f32_16x16x32_bf16 v[76:79], v[144:147], v[204:207], v[76:79]
	s_setprio 0
	s_setprio 1
	v_mfma_f32_16x16x32_bf16 v[120:123], v[148:151], v[164:167], v[120:123]
	v_mfma_f32_16x16x32_bf16 v[116:119], v[156:159], v[164:167], v[116:119]
	v_mfma_f32_16x16x32_bf16 v[104:107], v[148:151], v[172:175], v[104:107]
	v_mfma_f32_16x16x32_bf16 v[100:103], v[156:159], v[172:175], v[100:103]
	v_mfma_f32_16x16x32_bf16 v[88:91], v[148:151], v[180:183], v[88:91]
	v_mfma_f32_16x16x32_bf16 v[84:87], v[156:159], v[180:183], v[84:87]
	v_mfma_f32_16x16x32_bf16 v[72:75], v[148:151], v[200:203], v[72:75]
	v_mfma_f32_16x16x32_bf16 v[68:71], v[156:159], v[200:203], v[68:71]
	v_mfma_f32_16x16x32_bf16 v[120:123], v[152:155], v[168:171], v[120:123]
	v_mfma_f32_16x16x32_bf16 v[116:119], v[160:163], v[168:171], v[116:119]
	v_mfma_f32_16x16x32_bf16 v[104:107], v[152:155], v[176:179], v[104:107]
	v_mfma_f32_16x16x32_bf16 v[100:103], v[160:163], v[176:179], v[100:103]
	v_mfma_f32_16x16x32_bf16 v[88:91], v[152:155], v[184:187], v[88:91]
	v_mfma_f32_16x16x32_bf16 v[84:87], v[160:163], v[184:187], v[84:87]
	v_mfma_f32_16x16x32_bf16 v[72:75], v[152:155], v[204:207], v[72:75]
	v_mfma_f32_16x16x32_bf16 v[68:71], v[160:163], v[204:207], v[68:71]
	s_setprio 0
	s_barrier
	s_add_i32 s22, s56, s28
	v_lshl_add_u64 v[208:209], v[208:209], 0, s[76:77]
	s_mov_b32 m0, s22
	ds_read_b128 v[164:167], v217 offset:49152
	ds_read_b128 v[168:171], v217 offset:50176
	ds_read_b128 v[172:175], v217 offset:51200
	ds_read_b128 v[176:179], v217 offset:52224
	ds_read_b128 v[180:183], v217 offset:53248
	ds_read_b128 v[184:187], v217 offset:54272
	ds_read_b128 v[200:203], v217 offset:55296
	ds_read_b128 v[204:207], v217 offset:56320
	global_load_lds_dwordx4 v[208:209], off
	s_add_i32 m0, s22, 0x2000
	s_add_u32 s20, s20, 0x80080
	v_lshl_add_u64 v[208:209], v[210:211], 0, s[76:77]
	s_addc_u32 s21, s21, 0
	s_add_i32 s22, s57, s28
	global_load_lds_dwordx4 v[208:209], off
	v_lshl_add_u64 v[208:209], s[20:21], 0, v[192:193]
	s_mov_b32 m0, s22
	s_nop 0
	global_load_lds_dwordx4 v[208:209], off
	v_lshl_add_u64 v[208:209], s[20:21], 0, v[188:189]
	s_add_i32 m0, s22, 0x2000
	s_nop 0
	global_load_lds_dwordx4 v[208:209], off
	v_lshl_add_u64 v[208:209], v[220:221], 0, s[76:77]
	s_mov_b32 m0, s38
	s_nop 0
	global_load_lds_dwordx4 v[208:209], off
	v_lshl_add_u64 v[208:209], v[222:223], 0, s[76:77]
	s_mov_b32 m0, s39
	s_nop 0
	global_load_lds_dwordx4 v[208:209], off
	s_waitcnt vmcnt(8)
	s_waitcnt lgkmcnt(0)
	s_barrier
	s_setprio 1
	s_waitcnt lgkmcnt(0)
	v_mfma_f32_16x16x32_bf16 v[64:67], v[132:135], v[164:167], v[64:67]
	v_mfma_f32_16x16x32_bf16 v[60:63], v[140:143], v[164:167], v[60:63]
	v_mfma_f32_16x16x32_bf16 v[48:51], v[132:135], v[172:175], v[48:51]
	v_mfma_f32_16x16x32_bf16 v[44:47], v[140:143], v[172:175], v[44:47]
	v_mfma_f32_16x16x32_bf16 v[32:35], v[132:135], v[180:183], v[32:35]
	v_mfma_f32_16x16x32_bf16 v[28:31], v[140:143], v[180:183], v[28:31]
	v_mfma_f32_16x16x32_bf16 v[16:19], v[132:135], v[200:203], v[16:19]
	v_mfma_f32_16x16x32_bf16 v[12:15], v[140:143], v[200:203], v[12:15]
	v_mfma_f32_16x16x32_bf16 v[64:67], v[136:139], v[168:171], v[64:67]
	v_mfma_f32_16x16x32_bf16 v[60:63], v[144:147], v[168:171], v[60:63]
	v_mfma_f32_16x16x32_bf16 v[48:51], v[136:139], v[176:179], v[48:51]
	v_mfma_f32_16x16x32_bf16 v[44:47], v[144:147], v[176:179], v[44:47]
	v_mfma_f32_16x16x32_bf16 v[32:35], v[136:139], v[184:187], v[32:35]
	v_mfma_f32_16x16x32_bf16 v[28:31], v[144:147], v[184:187], v[28:31]
	v_mfma_f32_16x16x32_bf16 v[16:19], v[136:139], v[204:207], v[16:19]
	v_mfma_f32_16x16x32_bf16 v[12:15], v[144:147], v[204:207], v[12:15]
	s_setprio 0
	s_setprio 1
	v_mfma_f32_16x16x32_bf16 v[56:59], v[148:151], v[164:167], v[56:59]
	v_mfma_f32_16x16x32_bf16 v[52:55], v[156:159], v[164:167], v[52:55]
	v_mfma_f32_16x16x32_bf16 v[40:43], v[148:151], v[172:175], v[40:43]
	v_mfma_f32_16x16x32_bf16 v[36:39], v[156:159], v[172:175], v[36:39]
	v_mfma_f32_16x16x32_bf16 v[24:27], v[148:151], v[180:183], v[24:27]
	v_mfma_f32_16x16x32_bf16 v[20:23], v[156:159], v[180:183], v[20:23]
	v_mfma_f32_16x16x32_bf16 v[8:11], v[148:151], v[200:203], v[8:11]
	v_mfma_f32_16x16x32_bf16 v[4:7], v[156:159], v[200:203], v[4:7]
	v_mfma_f32_16x16x32_bf16 v[56:59], v[152:155], v[168:171], v[56:59]
	v_mfma_f32_16x16x32_bf16 v[52:55], v[160:163], v[168:171], v[52:55]
	v_mfma_f32_16x16x32_bf16 v[40:43], v[152:155], v[176:179], v[40:43]
	v_mfma_f32_16x16x32_bf16 v[36:39], v[160:163], v[176:179], v[36:39]
	s_add_i32 s52, s52, 2
	s_add_u32 s48, s48, 0x100
	s_addc_u32 s49, s49, 0
	s_add_u32 s18, s18, 0x100
	s_addc_u32 s19, s19, 0
	s_cmp_gt_u32 s52, 29
	v_mfma_f32_16x16x32_bf16 v[24:27], v[152:155], v[184:187], v[24:27]
	v_mfma_f32_16x16x32_bf16 v[20:23], v[160:163], v[184:187], v[20:23]
	v_mfma_f32_16x16x32_bf16 v[8:11], v[152:155], v[204:207], v[8:11]
	v_mfma_f32_16x16x32_bf16 v[4:7], v[160:163], v[204:207], v[4:7]
	s_setprio 0
	s_barrier
	s_cbranch_scc0 .LBB0_1229
	s_and_b64 vcc, exec, s[8:9]
	s_cbranch_vccz .LBB0_1232
	s_barrier

.LBB0_1336:
	s_add_i32 s17, 0, 0x10000
	v_add_u32_e32 v2, s17, v220
	s_add_i32 s41, 0, 0x14000
	ds_read_b128 v[28:31], v2
	ds_read_b128 v[32:35], v2 offset:1024
	ds_read_b128 v[36:39], v2 offset:2048
	ds_read_b128 v[40:43], v2 offset:3072
	v_add_u32_e32 v2, s41, v220
	ds_read_b128 v[44:47], v2
	ds_read_b128 v[48:51], v2 offset:1024
	ds_read_b128 v[52:55], v2 offset:2048
	ds_read_b128 v[56:59], v2 offset:3072
	v_lshl_add_u64 v[196:197], s[8:9], 0, v[232:233]
	s_add_i32 m0, s58, 0xc000
	ds_read_b128 v[92:95], v216
	ds_read_b128 v[96:99], v216 offset:1024
	ds_read_b128 v[100:103], v216 offset:2048
	ds_read_b128 v[104:107], v216 offset:3072
	ds_read_b128 v[108:111], v216 offset:4096
	ds_read_b128 v[112:115], v216 offset:5120
	ds_read_b128 v[116:119], v216 offset:6144
	ds_read_b128 v[120:123], v216 offset:7168
	global_load_lds_dwordx4 v[196:197], off
	v_lshl_add_u64 v[196:197], s[8:9], 0, v[230:231]
	s_add_i32 m0, s58, 0xe000
	s_nop 0
	global_load_lds_dwordx4 v[196:197], off
	s_add_u32 s10, s8, 0xfff80080
	s_addc_u32 s11, s9, -1
	s_cmp_eq_u32 s16, 28
	s_cselect_b32 s15, s18, s11
	s_cselect_b32 s14, s19, s10
	s_cselect_b32 s11, s22, s40
	s_cselect_b32 s10, s23, s39
	s_waitcnt vmcnt(8)
	s_waitcnt lgkmcnt(0)
	s_barrier
	s_setprio 1
	s_waitcnt lgkmcnt(0)
	v_mfma_f32_16x16x32_bf16 v[192:195], v[28:31], v[92:95], v[192:195]
	v_mfma_f32_16x16x32_bf16 v[160:163], v[36:39], v[92:95], v[160:163]
	v_mfma_f32_16x16x32_bf16 v[188:191], v[28:31], v[100:103], v[188:191]
	v_mfma_f32_16x16x32_bf16 v[152:155], v[36:39], v[100:103], v[152:155]
	v_mfma_f32_16x16x32_bf16 v[176:179], v[28:31], v[108:111], v[176:179]
	v_mfma_f32_16x16x32_bf16 v[144:147], v[36:39], v[108:111], v[144:147]
	v_mfma_f32_16x16x32_bf16 v[168:171], v[28:31], v[116:119], v[168:171]
	v_mfma_f32_16x16x32_bf16 v[136:139], v[36:39], v[116:119], v[136:139]
	v_mfma_f32_16x16x32_bf16 v[192:195], v[32:35], v[96:99], v[192:195]
	v_mfma_f32_16x16x32_bf16 v[160:163], v[40:43], v[96:99], v[160:163]
	v_mfma_f32_16x16x32_bf16 v[188:191], v[32:35], v[104:107], v[188:191]
	v_mfma_f32_16x16x32_bf16 v[152:155], v[40:43], v[104:107], v[152:155]
	v_mfma_f32_16x16x32_bf16 v[176:179], v[32:35], v[112:115], v[176:179]
	v_mfma_f32_16x16x32_bf16 v[144:147], v[40:43], v[112:115], v[144:147]
	v_mfma_f32_16x16x32_bf16 v[168:171], v[32:35], v[120:123], v[168:171]
	v_mfma_f32_16x16x32_bf16 v[136:139], v[40:43], v[120:123], v[136:139]
	s_setprio 0
	s_setprio 1
	v_mfma_f32_16x16x32_bf16 v[180:183], v[44:47], v[92:95], v[180:183]
	v_mfma_f32_16x16x32_bf16 v[92:95], v[52:55], v[92:95], v[156:159]
	v_mfma_f32_16x16x32_bf16 v[180:183], v[48:51], v[96:99], v[180:183]
	v_mfma_f32_16x16x32_bf16 v[92:95], v[56:59], v[96:99], v[92:95]
	v_mfma_f32_16x16x32_bf16 v[96:99], v[44:47], v[100:103], v[184:187]
	v_mfma_f32_16x16x32_bf16 v[100:103], v[52:55], v[100:103], v[148:151]
	v_mfma_f32_16x16x32_bf16 v[96:99], v[48:51], v[104:107], v[96:99]
	v_mfma_f32_16x16x32_bf16 v[100:103], v[56:59], v[104:107], v[100:103]
	v_mfma_f32_16x16x32_bf16 v[104:107], v[44:47], v[108:111], v[172:175]
	v_mfma_f32_16x16x32_bf16 v[108:111], v[52:55], v[108:111], v[140:143]
	v_mfma_f32_16x16x32_bf16 v[104:107], v[48:51], v[112:115], v[104:107]
	v_mfma_f32_16x16x32_bf16 v[108:111], v[56:59], v[112:115], v[108:111]
	v_mfma_f32_16x16x32_bf16 v[112:115], v[44:47], v[116:119], v[164:167]
	v_mfma_f32_16x16x32_bf16 v[116:119], v[52:55], v[116:119], v[132:135]
	v_mfma_f32_16x16x32_bf16 v[112:115], v[48:51], v[120:123], v[112:115]
	v_mfma_f32_16x16x32_bf16 v[116:119], v[56:59], v[120:123], v[116:119]
	s_setprio 0
	s_barrier
	s_add_i32 s17, s17, s54
	v_lshl_add_u64 v[234:235], s[10:11], 0, v[226:227]
	s_mov_b32 m0, s17
	ds_read_b128 v[120:123], v216 offset:16384
	ds_read_b128 v[132:135], v216 offset:17408
	ds_read_b128 v[140:143], v216 offset:18432
	ds_read_b128 v[148:151], v216 offset:19456
	ds_read_b128 v[156:159], v216 offset:20480
	ds_read_b128 v[164:167], v216 offset:21504
	ds_read_b128 v[172:175], v216 offset:22528
	ds_read_b128 v[184:187], v216 offset:23552
	global_load_lds_dwordx4 v[234:235], off
	s_add_i32 m0, s17, 0x2000
	s_add_u32 s42, s10, 0x80000
	v_lshl_add_u64 v[236:237], s[10:11], 0, v[222:223]
	s_addc_u32 s43, s11, 0
	s_add_i32 s17, s41, s54
	global_load_lds_dwordx4 v[236:237], off
	v_lshl_add_u64 v[196:197], s[42:43], 0, v[226:227]
	s_mov_b32 m0, s17
	v_lshl_add_u64 v[238:239], s[14:15], 0, v[228:229]
	global_load_lds_dwordx4 v[196:197], off
	v_lshl_add_u64 v[196:197], s[42:43], 0, v[222:223]
	s_add_i32 m0, s17, 0x2000
	v_lshl_add_u64 v[240:241], s[14:15], 0, v[224:225]
	global_load_lds_dwordx4 v[196:197], off
	s_mov_b32 m0, s58
	s_nop 0
	global_load_lds_dwordx4 v[238:239], off
	s_mov_b32 m0, s59
	s_nop 0
	global_load_lds_dwordx4 v[240:241], off
	s_waitcnt vmcnt(8)
	s_waitcnt lgkmcnt(0)
	s_barrier
	s_setprio 1
	s_waitcnt lgkmcnt(0)
	v_mfma_f32_16x16x32_bf16 v[128:131], v[28:31], v[120:123], v[128:131]
	v_mfma_f32_16x16x32_bf16 v[64:67], v[36:39], v[120:123], v[64:67]
	v_mfma_f32_16x16x32_bf16 v[88:91], v[28:31], v[140:143], v[88:91]
	v_mfma_f32_16x16x32_bf16 v[24:27], v[36:39], v[140:143], v[24:27]
	v_mfma_f32_16x16x32_bf16 v[80:83], v[28:31], v[156:159], v[80:83]
	v_mfma_f32_16x16x32_bf16 v[16:19], v[36:39], v[156:159], v[16:19]
	v_mfma_f32_16x16x32_bf16 v[8:11], v[36:39], v[172:175], v[8:11]
	v_mfma_f32_16x16x32_bf16 v[128:131], v[32:35], v[132:135], v[128:131]
	v_mfma_f32_16x16x32_bf16 v[64:67], v[40:43], v[132:135], v[64:67]
	v_mfma_f32_16x16x32_bf16 v[88:91], v[32:35], v[148:151], v[88:91]
	v_mfma_f32_16x16x32_bf16 v[24:27], v[40:43], v[148:151], v[24:27]
	v_mfma_f32_16x16x32_bf16 v[80:83], v[32:35], v[164:167], v[80:83]
	v_mfma_f32_16x16x32_bf16 v[16:19], v[40:43], v[164:167], v[16:19]
	v_mfma_f32_16x16x32_bf16 v[28:31], v[28:31], v[172:175], v[72:75]
	v_mfma_f32_16x16x32_bf16 v[8:11], v[40:43], v[184:187], v[8:11]
	v_mfma_f32_16x16x32_bf16 v[28:31], v[32:35], v[184:187], v[28:31]
	s_setprio 0
	s_setprio 1
	v_mfma_f32_16x16x32_bf16 v[36:39], v[52:55], v[120:123], v[60:63]
	v_mfma_f32_16x16x32_bf16 v[20:23], v[52:55], v[140:143], v[20:23]
	v_mfma_f32_16x16x32_bf16 v[60:63], v[44:47], v[156:159], v[76:79]
	v_mfma_f32_16x16x32_bf16 v[12:15], v[52:55], v[156:159], v[12:15]
	v_mfma_f32_16x16x32_bf16 v[4:7], v[52:55], v[172:175], v[4:7]
	v_mfma_f32_16x16x32_bf16 v[32:35], v[44:47], v[120:123], v[124:127]
	v_mfma_f32_16x16x32_bf16 v[40:43], v[44:47], v[140:143], v[84:87]
	v_mfma_f32_16x16x32_bf16 v[20:23], v[56:59], v[148:151], v[20:23]
	v_mfma_f32_16x16x32_bf16 v[76:79], v[48:51], v[164:167], v[60:63]
	v_mfma_f32_16x16x32_bf16 v[12:15], v[56:59], v[164:167], v[12:15]
	v_mfma_f32_16x16x32_bf16 v[44:47], v[44:47], v[172:175], v[68:71]
	v_mfma_f32_16x16x32_bf16 v[4:7], v[56:59], v[184:187], v[4:7]
	v_mfma_f32_16x16x32_bf16 v[32:35], v[48:51], v[132:135], v[32:35]
	v_mfma_f32_16x16x32_bf16 v[36:39], v[56:59], v[132:135], v[36:39]
	v_mfma_f32_16x16x32_bf16 v[40:43], v[48:51], v[148:151], v[40:43]
	v_mfma_f32_16x16x32_bf16 v[44:47], v[48:51], v[184:187], v[44:47]
	s_setprio 0
	s_barrier
	s_add_i32 s17, 0, 0x18000
	v_add_u32_e32 v2, s17, v220
	s_add_i32 s41, 0, 0x1c000
	ds_read_b128 v[48:51], v2
	ds_read_b128 v[52:55], v2 offset:1024
	ds_read_b128 v[56:59], v2 offset:2048
	ds_read_b128 v[60:63], v2 offset:3072
	v_add_u32_e32 v2, s41, v220
	ds_read_b128 v[68:71], v2
	ds_read_b128 v[120:123], v2 offset:1024
	ds_read_b128 v[196:199], v2 offset:2048
	ds_read_b128 v[200:203], v2 offset:3072
	s_add_u32 s14, s14, 0x80000
	s_addc_u32 s15, s15, 0
	s_mov_b32 m0, s60
	v_lshl_add_u64 v[148:149], s[14:15], 0, v[228:229]
	ds_read_b128 v[72:75], v216 offset:32768
	ds_read_b128 v[84:87], v216 offset:33792
	ds_read_b128 v[124:127], v216 offset:34816
	ds_read_b128 v[132:135], v216 offset:35840
	ds_read_b128 v[140:143], v216 offset:36864
	ds_read_b128 v[164:167], v216 offset:37888
	ds_read_b128 v[204:207], v216 offset:38912
	ds_read_b128 v[208:211], v216 offset:39936
	global_load_lds_dwordx4 v[148:149], off
	v_lshl_add_u64 v[148:149], s[14:15], 0, v[224:225]
	s_mov_b32 m0, s61
	s_nop 0
	global_load_lds_dwordx4 v[148:149], off
	s_waitcnt vmcnt(8)
	s_waitcnt lgkmcnt(0)
	s_barrier
	s_setprio 1
	s_waitcnt lgkmcnt(0)
	v_mfma_f32_16x16x32_bf16 v[148:151], v[48:51], v[72:75], v[192:195]
	v_mfma_f32_16x16x32_bf16 v[192:195], v[52:55], v[84:87], v[148:151]
	v_mfma_f32_16x16x32_bf16 v[148:151], v[56:59], v[72:75], v[160:163]
	v_mfma_f32_16x16x32_bf16 v[160:163], v[60:63], v[84:87], v[148:151]
	v_mfma_f32_16x16x32_bf16 v[148:151], v[48:51], v[124:127], v[188:191]
	v_mfma_f32_16x16x32_bf16 v[188:191], v[52:55], v[132:135], v[148:151]
	v_mfma_f32_16x16x32_bf16 v[148:151], v[56:59], v[124:127], v[152:155]
	v_mfma_f32_16x16x32_bf16 v[152:155], v[60:63], v[132:135], v[148:151]
	v_mfma_f32_16x16x32_bf16 v[148:151], v[48:51], v[140:143], v[176:179]
	v_mfma_f32_16x16x32_bf16 v[176:179], v[52:55], v[164:167], v[148:151]
	v_mfma_f32_16x16x32_bf16 v[144:147], v[56:59], v[140:143], v[144:147]
	v_mfma_f32_16x16x32_bf16 v[148:151], v[48:51], v[204:207], v[168:171]
	v_mfma_f32_16x16x32_bf16 v[136:139], v[56:59], v[204:207], v[136:139]
	v_mfma_f32_16x16x32_bf16 v[144:147], v[60:63], v[164:167], v[144:147]
	v_mfma_f32_16x16x32_bf16 v[168:171], v[52:55], v[208:211], v[148:151]
	v_mfma_f32_16x16x32_bf16 v[136:139], v[60:63], v[208:211], v[136:139]
	s_setprio 0
	s_setprio 1
	v_mfma_f32_16x16x32_bf16 v[148:151], v[68:71], v[72:75], v[180:183]
	v_mfma_f32_16x16x32_bf16 v[72:75], v[196:199], v[72:75], v[92:95]
	v_mfma_f32_16x16x32_bf16 v[156:159], v[200:203], v[84:87], v[72:75]
	v_mfma_f32_16x16x32_bf16 v[72:75], v[68:71], v[124:127], v[96:99]
	v_mfma_f32_16x16x32_bf16 v[184:187], v[120:123], v[132:135], v[72:75]
	v_mfma_f32_16x16x32_bf16 v[72:75], v[196:199], v[124:127], v[100:103]
	v_mfma_f32_16x16x32_bf16 v[180:183], v[120:123], v[84:87], v[148:151]
	v_mfma_f32_16x16x32_bf16 v[148:151], v[200:203], v[132:135], v[72:75]
	v_mfma_f32_16x16x32_bf16 v[72:75], v[68:71], v[140:143], v[104:107]
	v_mfma_f32_16x16x32_bf16 v[172:175], v[120:123], v[164:167], v[72:75]
	v_mfma_f32_16x16x32_bf16 v[72:75], v[196:199], v[140:143], v[108:111]
	v_mfma_f32_16x16x32_bf16 v[140:143], v[200:203], v[164:167], v[72:75]
	v_mfma_f32_16x16x32_bf16 v[72:75], v[68:71], v[204:207], v[112:115]
	v_mfma_f32_16x16x32_bf16 v[164:167], v[120:123], v[208:211], v[72:75]
	v_mfma_f32_16x16x32_bf16 v[72:75], v[196:199], v[204:207], v[116:119]
	v_mfma_f32_16x16x32_bf16 v[132:135], v[200:203], v[208:211], v[72:75]
	s_setprio 0
	s_barrier
	s_add_i32 s14, s17, s54
	s_nop 3
	v_lshl_add_u64 v[72:73], v[234:235], 0, s[20:21]
	s_mov_b32 m0, s14
	ds_read_b128 v[84:87], v216 offset:49152
	ds_read_b128 v[92:95], v216 offset:50176
	ds_read_b128 v[96:99], v216 offset:51200
	ds_read_b128 v[100:103], v216 offset:52224
	ds_read_b128 v[104:107], v216 offset:53248
	ds_read_b128 v[108:111], v216 offset:54272
	ds_read_b128 v[112:115], v216 offset:55296
	ds_read_b128 v[116:119], v216 offset:56320
	global_load_lds_dwordx4 v[72:73], off
	s_add_i32 m0, s14, 0x2000
	s_add_u32 s10, s10, 0x80080
	v_lshl_add_u64 v[72:73], v[236:237], 0, s[20:21]
	s_addc_u32 s11, s11, 0
	s_add_i32 s14, s41, s54
	global_load_lds_dwordx4 v[72:73], off
	v_lshl_add_u64 v[72:73], s[10:11], 0, v[226:227]
	s_mov_b32 m0, s14
	s_nop 0
	global_load_lds_dwordx4 v[72:73], off
	v_lshl_add_u64 v[72:73], s[10:11], 0, v[222:223]
	s_add_i32 m0, s14, 0x2000
	s_nop 0
	global_load_lds_dwordx4 v[72:73], off
	v_lshl_add_u64 v[72:73], v[238:239], 0, s[20:21]
	s_mov_b32 m0, s65
	s_nop 0
	global_load_lds_dwordx4 v[72:73], off
	v_lshl_add_u64 v[72:73], v[240:241], 0, s[20:21]
	s_mov_b32 m0, s66
	s_nop 0
	global_load_lds_dwordx4 v[72:73], off
	s_waitcnt vmcnt(8)
	s_waitcnt lgkmcnt(0)
	s_barrier
	s_setprio 1
	s_waitcnt lgkmcnt(0)
	v_mfma_f32_16x16x32_bf16 v[72:75], v[48:51], v[84:87], v[128:131]
	v_mfma_f32_16x16x32_bf16 v[128:131], v[52:55], v[92:95], v[72:75]
	v_mfma_f32_16x16x32_bf16 v[72:75], v[48:51], v[96:99], v[88:91]
	v_mfma_f32_16x16x32_bf16 v[64:67], v[56:59], v[84:87], v[64:67]
	v_mfma_f32_16x16x32_bf16 v[88:91], v[52:55], v[100:103], v[72:75]
	v_mfma_f32_16x16x32_bf16 v[24:27], v[56:59], v[96:99], v[24:27]
	v_mfma_f32_16x16x32_bf16 v[72:75], v[48:51], v[104:107], v[80:83]
	v_mfma_f32_16x16x32_bf16 v[16:19], v[56:59], v[104:107], v[16:19]
	v_mfma_f32_16x16x32_bf16 v[28:31], v[48:51], v[112:115], v[28:31]
	v_mfma_f32_16x16x32_bf16 v[8:11], v[56:59], v[112:115], v[8:11]
	v_mfma_f32_16x16x32_bf16 v[64:67], v[60:63], v[92:95], v[64:67]
	v_mfma_f32_16x16x32_bf16 v[24:27], v[60:63], v[100:103], v[24:27]
	v_mfma_f32_16x16x32_bf16 v[80:83], v[52:55], v[108:111], v[72:75]
	v_mfma_f32_16x16x32_bf16 v[16:19], v[60:63], v[108:111], v[16:19]
	v_mfma_f32_16x16x32_bf16 v[72:75], v[52:55], v[116:119], v[28:31]
	v_mfma_f32_16x16x32_bf16 v[8:11], v[60:63], v[116:119], v[8:11]
	s_setprio 0
	s_setprio 1
	v_mfma_f32_16x16x32_bf16 v[28:31], v[68:71], v[84:87], v[32:35]
	v_mfma_f32_16x16x32_bf16 v[124:127], v[120:123], v[92:95], v[28:31]
	v_mfma_f32_16x16x32_bf16 v[28:31], v[196:199], v[84:87], v[36:39]
	v_mfma_f32_16x16x32_bf16 v[60:63], v[200:203], v[92:95], v[28:31]
	v_mfma_f32_16x16x32_bf16 v[28:31], v[68:71], v[96:99], v[40:43]
	v_mfma_f32_16x16x32_bf16 v[84:87], v[120:123], v[100:103], v[28:31]
	v_mfma_f32_16x16x32_bf16 v[28:31], v[68:71], v[104:107], v[76:79]
	v_mfma_f32_16x16x32_bf16 v[20:23], v[196:199], v[96:99], v[20:23]
	v_mfma_f32_16x16x32_bf16 v[76:79], v[120:123], v[108:111], v[28:31]
	v_mfma_f32_16x16x32_bf16 v[12:15], v[196:199], v[104:107], v[12:15]
	v_mfma_f32_16x16x32_bf16 v[28:31], v[68:71], v[112:115], v[44:47]
	v_mfma_f32_16x16x32_bf16 v[4:7], v[196:199], v[112:115], v[4:7]
	s_add_i32 s16, s16, 2
	s_add_u32 s39, s39, 0x100
	s_addc_u32 s40, s40, 0
	s_add_u32 s8, s8, 0x100
	s_addc_u32 s9, s9, 0
	s_cmp_gt_u32 s16, 29
	v_mfma_f32_16x16x32_bf16 v[20:23], v[200:203], v[100:103], v[20:23]
	v_mfma_f32_16x16x32_bf16 v[12:15], v[200:203], v[108:111], v[12:15]
	v_mfma_f32_16x16x32_bf16 v[68:71], v[120:123], v[116:119], v[28:31]
	v_mfma_f32_16x16x32_bf16 v[4:7], v[200:203], v[116:119], v[4:7]
	s_setprio 0
	s_barrier
	s_cbranch_scc0 .LBB0_1336
	v_readlane_b32 s8, v255, 6
	v_readlane_b32 s9, v255, 7
	s_and_b64 vcc, exec, s[8:9]
	s_mov_b32 s81, 0xb000
	s_cbranch_vccz .LBB0_1339
	s_barrier

.LBB0_1504:
	s_add_i32 s58, 0, 0x10000
	v_add_u32_e32 v2, s58, v216
	s_add_i32 s59, 0, 0x14000
	ds_read_b128 v[124:127], v2
	ds_read_b128 v[128:131], v2 offset:1024
	ds_read_b128 v[132:135], v2 offset:2048
	ds_read_b128 v[136:139], v2 offset:3072
	v_add_u32_e32 v2, s59, v216
	ds_read_b128 v[148:151], v2
	ds_read_b128 v[152:155], v2 offset:1024
	ds_read_b128 v[156:159], v2 offset:2048
	ds_read_b128 v[160:163], v2 offset:3072
	v_lshl_add_u64 v[208:209], s[22:23], 0, v[198:199]
	s_add_i32 m0, s31, 0xc000
	ds_read_b128 v[164:167], v217
	ds_read_b128 v[168:171], v217 offset:1024
	ds_read_b128 v[172:175], v217 offset:2048
	ds_read_b128 v[176:179], v217 offset:3072
	ds_read_b128 v[180:183], v217 offset:4096
	ds_read_b128 v[184:187], v217 offset:5120
	ds_read_b128 v[200:203], v217 offset:6144
	ds_read_b128 v[204:207], v217 offset:7168
	global_load_lds_dwordx4 v[208:209], off
	v_lshl_add_u64 v[208:209], s[22:23], 0, v[196:197]
	s_add_i32 m0, s31, 0xe000
	s_nop 0
	global_load_lds_dwordx4 v[208:209], off
	s_add_u32 s4, s22, 0x100
	s_addc_u32 s5, s23, 0
	s_cmpk_eq_i32 s57, 0x54
	s_cselect_b32 s27, s19, s5
	s_cselect_b32 s26, s18, s4
	s_cselect_b32 s25, s21, s56
	s_cselect_b32 s24, s20, s52
	s_waitcnt vmcnt(8)
	s_waitcnt lgkmcnt(0)
	s_barrier
	s_setprio 1
	s_waitcnt lgkmcnt(0)
	v_mfma_f32_16x16x32_bf16 v[144:147], v[124:127], v[164:167], v[144:147]
	v_mfma_f32_16x16x32_bf16 v[140:143], v[132:135], v[164:167], v[140:143]
	v_mfma_f32_16x16x32_bf16 v[112:115], v[124:127], v[172:175], v[112:115]
	v_mfma_f32_16x16x32_bf16 v[108:111], v[132:135], v[172:175], v[108:111]
	v_mfma_f32_16x16x32_bf16 v[96:99], v[124:127], v[180:183], v[96:99]
	v_mfma_f32_16x16x32_bf16 v[92:95], v[132:135], v[180:183], v[92:95]
	v_mfma_f32_16x16x32_bf16 v[80:83], v[124:127], v[200:203], v[80:83]
	v_mfma_f32_16x16x32_bf16 v[76:79], v[132:135], v[200:203], v[76:79]
	v_mfma_f32_16x16x32_bf16 v[144:147], v[128:131], v[168:171], v[144:147]
	v_mfma_f32_16x16x32_bf16 v[140:143], v[136:139], v[168:171], v[140:143]
	v_mfma_f32_16x16x32_bf16 v[112:115], v[128:131], v[176:179], v[112:115]
	v_mfma_f32_16x16x32_bf16 v[108:111], v[136:139], v[176:179], v[108:111]
	v_mfma_f32_16x16x32_bf16 v[96:99], v[128:131], v[184:187], v[96:99]
	v_mfma_f32_16x16x32_bf16 v[92:95], v[136:139], v[184:187], v[92:95]
	v_mfma_f32_16x16x32_bf16 v[80:83], v[128:131], v[204:207], v[80:83]
	v_mfma_f32_16x16x32_bf16 v[76:79], v[136:139], v[204:207], v[76:79]
	s_setprio 0
	s_setprio 1
	v_mfma_f32_16x16x32_bf16 v[120:123], v[148:151], v[164:167], v[120:123]
	v_mfma_f32_16x16x32_bf16 v[116:119], v[156:159], v[164:167], v[116:119]
	v_mfma_f32_16x16x32_bf16 v[104:107], v[148:151], v[172:175], v[104:107]
	v_mfma_f32_16x16x32_bf16 v[100:103], v[156:159], v[172:175], v[100:103]
	v_mfma_f32_16x16x32_bf16 v[88:91], v[148:151], v[180:183], v[88:91]
	v_mfma_f32_16x16x32_bf16 v[84:87], v[156:159], v[180:183], v[84:87]
	v_mfma_f32_16x16x32_bf16 v[72:75], v[148:151], v[200:203], v[72:75]
	v_mfma_f32_16x16x32_bf16 v[68:71], v[156:159], v[200:203], v[68:71]
	v_mfma_f32_16x16x32_bf16 v[120:123], v[152:155], v[168:171], v[120:123]
	v_mfma_f32_16x16x32_bf16 v[116:119], v[160:163], v[168:171], v[116:119]
	v_mfma_f32_16x16x32_bf16 v[104:107], v[152:155], v[176:179], v[104:107]
	v_mfma_f32_16x16x32_bf16 v[100:103], v[160:163], v[176:179], v[100:103]
	v_mfma_f32_16x16x32_bf16 v[88:91], v[152:155], v[184:187], v[88:91]
	v_mfma_f32_16x16x32_bf16 v[84:87], v[160:163], v[184:187], v[84:87]
	v_mfma_f32_16x16x32_bf16 v[72:75], v[152:155], v[204:207], v[72:75]
	v_mfma_f32_16x16x32_bf16 v[68:71], v[160:163], v[204:207], v[68:71]
	s_setprio 0
	s_barrier
	s_add_i32 s22, s58, s28
	v_lshl_add_u64 v[208:209], s[24:25], 0, v[192:193]
	s_mov_b32 m0, s22
	ds_read_b128 v[164:167], v217 offset:16384
	ds_read_b128 v[168:171], v217 offset:17408
	ds_read_b128 v[172:175], v217 offset:18432
	ds_read_b128 v[176:179], v217 offset:19456
	ds_read_b128 v[180:183], v217 offset:20480
	ds_read_b128 v[184:187], v217 offset:21504
	ds_read_b128 v[200:203], v217 offset:22528
	ds_read_b128 v[204:207], v217 offset:23552
	global_load_lds_dwordx4 v[208:209], off
	s_add_i32 m0, s22, 0x2000
	s_add_u32 s22, s24, 0x160000
	v_lshl_add_u64 v[210:211], s[24:25], 0, v[188:189]
	s_addc_u32 s23, s25, 0
	s_add_i32 s58, s59, s28
	global_load_lds_dwordx4 v[210:211], off
	v_lshl_add_u64 v[220:221], s[22:23], 0, v[192:193]
	s_mov_b32 m0, s58
	v_lshl_add_u64 v[222:223], s[26:27], 0, v[190:191]
	global_load_lds_dwordx4 v[220:221], off
	v_lshl_add_u64 v[220:221], s[22:23], 0, v[188:189]
	s_add_i32 m0, s58, 0x2000
	s_nop 0
	global_load_lds_dwordx4 v[220:221], off
	v_lshl_add_u64 v[220:221], s[26:27], 0, v[194:195]
	s_mov_b32 m0, s31
	s_nop 0
	global_load_lds_dwordx4 v[220:221], off
	s_mov_b32 m0, s34
	s_nop 0
	global_load_lds_dwordx4 v[222:223], off
	s_waitcnt vmcnt(8)
	s_waitcnt lgkmcnt(0)
	s_barrier
	s_setprio 1
	s_waitcnt lgkmcnt(0)
	v_mfma_f32_16x16x32_bf16 v[64:67], v[124:127], v[164:167], v[64:67]
	v_mfma_f32_16x16x32_bf16 v[60:63], v[132:135], v[164:167], v[60:63]
	v_mfma_f32_16x16x32_bf16 v[48:51], v[124:127], v[172:175], v[48:51]
	v_mfma_f32_16x16x32_bf16 v[44:47], v[132:135], v[172:175], v[44:47]
	v_mfma_f32_16x16x32_bf16 v[32:35], v[124:127], v[180:183], v[32:35]
	v_mfma_f32_16x16x32_bf16 v[28:31], v[132:135], v[180:183], v[28:31]
	v_mfma_f32_16x16x32_bf16 v[16:19], v[124:127], v[200:203], v[16:19]
	v_mfma_f32_16x16x32_bf16 v[12:15], v[132:135], v[200:203], v[12:15]
	v_mfma_f32_16x16x32_bf16 v[64:67], v[128:131], v[168:171], v[64:67]
	v_mfma_f32_16x16x32_bf16 v[60:63], v[136:139], v[168:171], v[60:63]
	v_mfma_f32_16x16x32_bf16 v[48:51], v[128:131], v[176:179], v[48:51]
	v_mfma_f32_16x16x32_bf16 v[44:47], v[136:139], v[176:179], v[44:47]
	v_mfma_f32_16x16x32_bf16 v[32:35], v[128:131], v[184:187], v[32:35]
	v_mfma_f32_16x16x32_bf16 v[28:31], v[136:139], v[184:187], v[28:31]
	v_mfma_f32_16x16x32_bf16 v[16:19], v[128:131], v[204:207], v[16:19]
	v_mfma_f32_16x16x32_bf16 v[12:15], v[136:139], v[204:207], v[12:15]
	s_setprio 0
	s_setprio 1
	v_mfma_f32_16x16x32_bf16 v[56:59], v[148:151], v[164:167], v[56:59]
	v_mfma_f32_16x16x32_bf16 v[52:55], v[156:159], v[164:167], v[52:55]
	v_mfma_f32_16x16x32_bf16 v[40:43], v[148:151], v[172:175], v[40:43]
	v_mfma_f32_16x16x32_bf16 v[36:39], v[156:159], v[172:175], v[36:39]
	v_mfma_f32_16x16x32_bf16 v[24:27], v[148:151], v[180:183], v[24:27]
	v_mfma_f32_16x16x32_bf16 v[20:23], v[156:159], v[180:183], v[20:23]
	v_mfma_f32_16x16x32_bf16 v[8:11], v[148:151], v[200:203], v[8:11]
	v_mfma_f32_16x16x32_bf16 v[4:7], v[156:159], v[200:203], v[4:7]
	v_mfma_f32_16x16x32_bf16 v[56:59], v[152:155], v[168:171], v[56:59]
	v_mfma_f32_16x16x32_bf16 v[52:55], v[160:163], v[168:171], v[52:55]
	v_mfma_f32_16x16x32_bf16 v[40:43], v[152:155], v[176:179], v[40:43]
	v_mfma_f32_16x16x32_bf16 v[36:39], v[160:163], v[176:179], v[36:39]
	v_mfma_f32_16x16x32_bf16 v[24:27], v[152:155], v[184:187], v[24:27]
	v_mfma_f32_16x16x32_bf16 v[20:23], v[160:163], v[184:187], v[20:23]
	v_mfma_f32_16x16x32_bf16 v[8:11], v[152:155], v[204:207], v[8:11]
	v_mfma_f32_16x16x32_bf16 v[4:7], v[160:163], v[204:207], v[4:7]
	s_setprio 0
	s_barrier
	s_add_i32 s58, 0, 0x18000
	v_add_u32_e32 v2, s58, v216
	s_add_i32 s59, 0, 0x1c000
	ds_read_b128 v[124:127], v2
	ds_read_b128 v[128:131], v2 offset:1024
	ds_read_b128 v[132:135], v2 offset:2048
	ds_read_b128 v[136:139], v2 offset:3072
	v_add_u32_e32 v2, s59, v216
	ds_read_b128 v[148:151], v2
	ds_read_b128 v[152:155], v2 offset:1024
	ds_read_b128 v[156:159], v2 offset:2048
	ds_read_b128 v[160:163], v2 offset:3072
	s_add_u32 s22, s26, 0x160000
	s_addc_u32 s23, s27, 0
	s_mov_b32 m0, s35
	v_lshl_add_u64 v[224:225], s[22:23], 0, v[194:195]
	ds_read_b128 v[164:167], v217 offset:32768
	ds_read_b128 v[168:171], v217 offset:33792
	ds_read_b128 v[172:175], v217 offset:34816
	ds_read_b128 v[176:179], v217 offset:35840
	ds_read_b128 v[180:183], v217 offset:36864
	ds_read_b128 v[184:187], v217 offset:37888
	ds_read_b128 v[200:203], v217 offset:38912
	ds_read_b128 v[204:207], v217 offset:39936
	global_load_lds_dwordx4 v[224:225], off
	v_lshl_add_u64 v[224:225], s[22:23], 0, v[190:191]
	s_mov_b32 m0, s36
	s_nop 0
	global_load_lds_dwordx4 v[224:225], off
	s_waitcnt vmcnt(8)
	s_waitcnt lgkmcnt(0)
	s_barrier
	s_setprio 1
	s_waitcnt lgkmcnt(0)
	v_mfma_f32_16x16x32_bf16 v[144:147], v[124:127], v[164:167], v[144:147]
	v_mfma_f32_16x16x32_bf16 v[140:143], v[132:135], v[164:167], v[140:143]
	v_mfma_f32_16x16x32_bf16 v[112:115], v[124:127], v[172:175], v[112:115]
	v_mfma_f32_16x16x32_bf16 v[108:111], v[132:135], v[172:175], v[108:111]
	v_mfma_f32_16x16x32_bf16 v[96:99], v[124:127], v[180:183], v[96:99]
	v_mfma_f32_16x16x32_bf16 v[92:95], v[132:135], v[180:183], v[92:95]
	v_mfma_f32_16x16x32_bf16 v[80:83], v[124:127], v[200:203], v[80:83]
	v_mfma_f32_16x16x32_bf16 v[76:79], v[132:135], v[200:203], v[76:79]
	v_mfma_f32_16x16x32_bf16 v[144:147], v[128:131], v[168:171], v[144:147]
	v_mfma_f32_16x16x32_bf16 v[140:143], v[136:139], v[168:171], v[140:143]
	v_mfma_f32_16x16x32_bf16 v[112:115], v[128:131], v[176:179], v[112:115]
	v_mfma_f32_16x16x32_bf16 v[108:111], v[136:139], v[176:179], v[108:111]
	v_mfma_f32_16x16x32_bf16 v[96:99], v[128:131], v[184:187], v[96:99]
	v_mfma_f32_16x16x32_bf16 v[92:95], v[136:139], v[184:187], v[92:95]
	v_mfma_f32_16x16x32_bf16 v[80:83], v[128:131], v[204:207], v[80:83]
	v_mfma_f32_16x16x32_bf16 v[76:79], v[136:139], v[204:207], v[76:79]
	s_setprio 0
	s_setprio 1
	v_mfma_f32_16x16x32_bf16 v[120:123], v[148:151], v[164:167], v[120:123]
	v_mfma_f32_16x16x32_bf16 v[116:119], v[156:159], v[164:167], v[116:119]
	v_mfma_f32_16x16x32_bf16 v[104:107], v[148:151], v[172:175], v[104:107]
	v_mfma_f32_16x16x32_bf16 v[100:103], v[156:159], v[172:175], v[100:103]
	v_mfma_f32_16x16x32_bf16 v[88:91], v[148:151], v[180:183], v[88:91]
	v_mfma_f32_16x16x32_bf16 v[84:87], v[156:159], v[180:183], v[84:87]
	v_mfma_f32_16x16x32_bf16 v[72:75], v[148:151], v[200:203], v[72:75]
	v_mfma_f32_16x16x32_bf16 v[68:71], v[156:159], v[200:203], v[68:71]
	v_mfma_f32_16x16x32_bf16 v[120:123], v[152:155], v[168:171], v[120:123]
	v_mfma_f32_16x16x32_bf16 v[116:119], v[160:163], v[168:171], v[116:119]
	v_mfma_f32_16x16x32_bf16 v[104:107], v[152:155], v[176:179], v[104:107]
	v_mfma_f32_16x16x32_bf16 v[100:103], v[160:163], v[176:179], v[100:103]
	v_mfma_f32_16x16x32_bf16 v[88:91], v[152:155], v[184:187], v[88:91]
	v_mfma_f32_16x16x32_bf16 v[84:87], v[160:163], v[184:187], v[84:87]
	v_mfma_f32_16x16x32_bf16 v[72:75], v[152:155], v[204:207], v[72:75]
	v_mfma_f32_16x16x32_bf16 v[68:71], v[160:163], v[204:207], v[68:71]
	s_setprio 0
	s_barrier
	s_add_i32 s22, s58, s28
	v_lshl_add_u64 v[208:209], v[208:209], 0, s[76:77]
	s_mov_b32 m0, s22
	ds_read_b128 v[164:167], v217 offset:49152
	ds_read_b128 v[168:171], v217 offset:50176
	ds_read_b128 v[172:175], v217 offset:51200
	ds_read_b128 v[176:179], v217 offset:52224
	ds_read_b128 v[180:183], v217 offset:53248
	ds_read_b128 v[184:187], v217 offset:54272
	ds_read_b128 v[200:203], v217 offset:55296
	ds_read_b128 v[204:207], v217 offset:56320
	global_load_lds_dwordx4 v[208:209], off
	s_add_i32 m0, s22, 0x2000
	s_add_u32 s22, s24, 0x160080
	v_lshl_add_u64 v[208:209], v[210:211], 0, s[76:77]
	s_addc_u32 s23, s25, 0
	s_add_i32 s24, s59, s28
	global_load_lds_dwordx4 v[208:209], off
	v_lshl_add_u64 v[208:209], s[22:23], 0, v[192:193]
	s_mov_b32 m0, s24
	s_nop 0
	global_load_lds_dwordx4 v[208:209], off
	v_lshl_add_u64 v[208:209], s[22:23], 0, v[188:189]
	s_add_i32 m0, s24, 0x2000
	s_nop 0
	global_load_lds_dwordx4 v[208:209], off
	v_lshl_add_u64 v[208:209], v[220:221], 0, s[76:77]
	s_mov_b32 m0, s40
	s_nop 0
	global_load_lds_dwordx4 v[208:209], off
	v_lshl_add_u64 v[208:209], v[222:223], 0, s[76:77]
	s_mov_b32 m0, s41
	s_nop 0
	global_load_lds_dwordx4 v[208:209], off
	s_waitcnt vmcnt(8)
	s_waitcnt lgkmcnt(0)
	s_barrier
	s_setprio 1
	s_waitcnt lgkmcnt(0)
	v_mfma_f32_16x16x32_bf16 v[64:67], v[124:127], v[164:167], v[64:67]
	v_mfma_f32_16x16x32_bf16 v[60:63], v[132:135], v[164:167], v[60:63]
	v_mfma_f32_16x16x32_bf16 v[48:51], v[124:127], v[172:175], v[48:51]
	v_mfma_f32_16x16x32_bf16 v[44:47], v[132:135], v[172:175], v[44:47]
	v_mfma_f32_16x16x32_bf16 v[32:35], v[124:127], v[180:183], v[32:35]
	v_mfma_f32_16x16x32_bf16 v[28:31], v[132:135], v[180:183], v[28:31]
	v_mfma_f32_16x16x32_bf16 v[16:19], v[124:127], v[200:203], v[16:19]
	v_mfma_f32_16x16x32_bf16 v[12:15], v[132:135], v[200:203], v[12:15]
	v_mfma_f32_16x16x32_bf16 v[64:67], v[128:131], v[168:171], v[64:67]
	v_mfma_f32_16x16x32_bf16 v[60:63], v[136:139], v[168:171], v[60:63]
	v_mfma_f32_16x16x32_bf16 v[48:51], v[128:131], v[176:179], v[48:51]
	v_mfma_f32_16x16x32_bf16 v[44:47], v[136:139], v[176:179], v[44:47]
	v_mfma_f32_16x16x32_bf16 v[32:35], v[128:131], v[184:187], v[32:35]
	v_mfma_f32_16x16x32_bf16 v[28:31], v[136:139], v[184:187], v[28:31]
	v_mfma_f32_16x16x32_bf16 v[16:19], v[128:131], v[204:207], v[16:19]
	v_mfma_f32_16x16x32_bf16 v[12:15], v[136:139], v[204:207], v[12:15]
	s_setprio 0
	s_setprio 1
	v_mfma_f32_16x16x32_bf16 v[56:59], v[148:151], v[164:167], v[56:59]
	v_mfma_f32_16x16x32_bf16 v[52:55], v[156:159], v[164:167], v[52:55]
	v_mfma_f32_16x16x32_bf16 v[40:43], v[148:151], v[172:175], v[40:43]
	v_mfma_f32_16x16x32_bf16 v[36:39], v[156:159], v[172:175], v[36:39]
	v_mfma_f32_16x16x32_bf16 v[24:27], v[148:151], v[180:183], v[24:27]
	v_mfma_f32_16x16x32_bf16 v[20:23], v[156:159], v[180:183], v[20:23]
	v_mfma_f32_16x16x32_bf16 v[8:11], v[148:151], v[200:203], v[8:11]
	v_mfma_f32_16x16x32_bf16 v[4:7], v[156:159], v[200:203], v[4:7]
	v_mfma_f32_16x16x32_bf16 v[56:59], v[152:155], v[168:171], v[56:59]
	v_mfma_f32_16x16x32_bf16 v[52:55], v[160:163], v[168:171], v[52:55]
	v_mfma_f32_16x16x32_bf16 v[40:43], v[152:155], v[176:179], v[40:43]
	v_mfma_f32_16x16x32_bf16 v[36:39], v[160:163], v[176:179], v[36:39]
	s_add_i32 s57, s57, 2
	s_add_u32 s52, s52, 0x100
	s_addc_u32 s56, s56, 0
	s_cmpk_gt_u32 s57, 0x55
	s_mov_b64 s[22:23], s[4:5]
	v_mfma_f32_16x16x32_bf16 v[24:27], v[152:155], v[184:187], v[24:27]
	v_mfma_f32_16x16x32_bf16 v[20:23], v[160:163], v[184:187], v[20:23]
	v_mfma_f32_16x16x32_bf16 v[8:11], v[152:155], v[204:207], v[8:11]
	v_mfma_f32_16x16x32_bf16 v[4:7], v[160:163], v[204:207], v[4:7]
	s_setprio 0
	s_barrier
	s_cbranch_scc0 .LBB0_1504
	s_and_b64 vcc, exec, s[16:17]
	s_cbranch_vccz .LBB0_1507
	s_barrier
